# baseline (speedup 1.0000x reference)
; __device__ __forceinline__ unsigned cvt_pk(float lo, float hi) { unsigned r; asm("v_cvt_pk_bf16_f32 %0, %1, %2" : "=v"(r) : "v"(lo), "v"(hi)); return r; }
; __device__ __forceinline__ float bflo(unsigned w) { return __uint_as_float(w << 16); }
; __device__ __forceinline__ float bfhi(unsigned w) { return __uint_as_float(w & 0xffff0000u); }
; __device__ __forceinline__ void gla_c_item(unsigned char* lds, const Params& p, int item, bool dry) {
;     ...
;     for (int tb = 0; tb < 4; ++tb) { const int t = 16 * tb + li; float tot = 0.f;
; #pragma unroll
;         for (int w8 = 0; w8 < 8; ++w8) tot += red[w8 * 64 + t];
;         const float rinv = 1.0f / sqrtf(tot * (1.f / 256.f) + LN_EPS);
;         if (t < nvalid && !dry) {
; #pragma unroll
;             for (int v = 0; v < 2; ++v) { const int vdim = 16 * (2 * wave + v) + 4 * fq;
;                 const u32x2 ogw = *(const u32x2*)(P + (size_t)(row0 + t) * NPROJ + C_OG + h * 256 + vdim);
;                 const f32x4 g4 = *(const f32x4*)(gn + vdim);
;                 const float og[4] = {bflo(ogw.x), bfhi(ogw.x), bflo(ogw.y), bfhi(ogw.y)}; float r4[4];
; #pragma unroll
;                 for (int r = 0; r < 4; ++r) r4[r] = o[v][tb][r] * rinv * g4[r] * (og[r] * __builtin_amdgcn_rcpf(1.f + __expf(-og[r])));
;                 u32x2 w; w.x = cvt_pk(r4[0], r4[1]); w.y = cvt_pk(r4[2], r4[3]);
;                 *(u32x2*)(P + (size_t)(row0 + t) * NPROJ + C_VA + h * 256 + vdim) = w; }
.LBB0_1031:
	s_or_b64 exec, exec, s[0:1]
	v_readlane_b32 s56, v251, 34
	v_readlane_b32 s10, v251, 50
	s_lshl_b32 s0, s16, 2
	v_readlane_b32 s58, v251, 36
	v_readlane_b32 s11, v251, 51
	v_readlane_b32 s59, v251, 37
	s_add_u32 s0, s58, s0
	v_or_b32_e32 v40, s6, v32
	v_add_u32_e32 v53, s75, v52
	v_mov_b64_e32 v[46:47], s[10:11]
	s_addc_u32 s1, s59, 0
	v_mad_i64_i32 v[32:33], s[10:11], v53, s23, v[46:47]
	s_lshl_b32 s6, s16, 1
	v_ashrrev_i32_e32 v41, 31, v40
	v_lshl_add_u64 v[42:43], v[32:33], 0, s[6:7]
	v_lshlrev_b64 v[54:55], 1, v[40:41]
	v_lshl_add_u64 v[42:43], v[42:43], 0, v[54:55]
	s_waitcnt lgkmcnt(0)
	s_barrier
	v_lshl_add_u64 v[38:39], v[40:41], 2, s[0:1]
	global_load_dwordx2 v[44:45], v[42:43], off offset:2048
	global_load_dwordx4 v[32:35], v[38:39], off
	global_load_dwordx4 v[200:203], v[38:39], off
	global_load_dwordx4 v[204:207], v[38:39], off offset:64
	v_lshl_add_u32 v36, v52, 2, 0
	v_add_u32_e32 v58, 0x1800, v36
	v_add_u32_e32 v66, 0x1c00, v36
	v_add_u32_e32 v70, 0x2000, v36
	ds_read2_b32 v[56:57], v58 offset0:128 offset1:144
	ds_read2_b32 v[58:59], v58 offset0:192 offset1:208
	ds_read2_b32 v[60:61], v66 offset1:16
	ds_read2_b32 v[62:63], v66 offset0:64 offset1:80
	ds_read2_b32 v[64:65], v66 offset0:128 offset1:144
	ds_read2_b32 v[66:67], v66 offset0:192 offset1:208
	ds_read2_b32 v[68:69], v70 offset1:16
	ds_read2_b32 v[70:71], v70 offset0:64 offset1:80
	s_waitcnt lgkmcnt(7)
	v_add_f32_e32 v56, 0, v56
	s_waitcnt lgkmcnt(6)
	v_add_f32_e32 v56, v56, v58
	s_waitcnt lgkmcnt(5)
	v_add_f32_e32 v56, v56, v60
	s_waitcnt lgkmcnt(4)
	v_add_f32_e32 v56, v56, v62
	s_waitcnt lgkmcnt(3)
	v_add_f32_e32 v56, v56, v64
	s_waitcnt lgkmcnt(2)
	v_add_f32_e32 v56, v56, v66
	s_waitcnt lgkmcnt(1)
	v_add_f32_e32 v56, v56, v68
	s_waitcnt lgkmcnt(0)
	v_add_f32_e32 v56, v56, v70
	v_fmamk_f32 v56, v56, 0x3b800000, v49
	v_mul_f32_e32 v58, 0x4f800000, v56
	v_cmp_gt_f32_e32 vcc, s74, v56
	v_add_u32_e32 v53, 16, v53
	v_mad_i64_i32 v[46:47], s[0:1], v53, s23, v[46:47]
	v_cndmask_b32_e32 v56, v56, v58, vcc
	v_sqrt_f32_e32 v58, v56
	v_lshl_add_u64 v[46:47], v[46:47], 0, s[6:7]
	v_lshl_add_u64 v[46:47], v[46:47], 0, v[54:55]
	v_readlane_b32 s57, v251, 35
	v_add_u32_e32 v53, -1, v58
	v_add_u32_e32 v54, 1, v58
	v_fma_f32 v55, -v53, v58, v56
	v_fma_f32 v60, -v54, v58, v56
	v_cmp_ge_f32_e64 s[0:1], 0, v55
	v_readlane_b32 s60, v251, 38
	v_readlane_b32 s61, v251, 39
	v_cndmask_b32_e64 v53, v58, v53, s[0:1]
	v_cmp_lt_f32_e64 s[0:1], 0, v60
	v_readlane_b32 s62, v251, 40
	v_readlane_b32 s63, v251, 41
	v_cndmask_b32_e64 v53, v53, v54, s[0:1]
	v_mul_f32_e32 v54, 0x37800000, v53
	v_cndmask_b32_e32 v53, v53, v54, vcc
	v_cmp_class_f32_e32 vcc, v56, v50
	global_load_dwordx2 v[54:55], v[42:43], off offset:2080
	global_load_dwordx2 v[72:73], v[46:47], off offset:2048
	global_load_dwordx2 v[74:75], v[46:47], off offset:2080
	v_cndmask_b32_e32 v53, v53, v56, vcc
	v_div_scale_f32 v56, s[0:1], v53, v53, 1.0
	v_rcp_f32_e32 v58, v56
	v_div_scale_f32 v60, vcc, 1.0, v53, 1.0
	v_readlane_b32 s64, v251, 42
	v_fma_f32 v62, -v56, v58, 1.0
	v_fmac_f32_e32 v58, v62, v58
	v_mul_f32_e32 v62, v60, v58
	v_fma_f32 v64, -v56, v62, v60
	v_fmac_f32_e32 v62, v64, v58
	v_fma_f32 v56, -v56, v62, v60
	v_div_fmas_f32 v56, v56, v58, v62
	v_div_fixup_f32 v53, v56, v53, 1.0
	v_mul_f32_e32 v76, v25, v53
	v_mul_f32_e32 v24, v24, v53
	v_mul_f32_e32 v80, v26, v53
	v_mul_f32_e32 v28, v28, v53
	v_mul_f32_e32 v30, v30, v53
	v_readlane_b32 s65, v251, 43
	v_readlane_b32 s66, v251, 44
	v_readlane_b32 s67, v251, 45
	v_readlane_b32 s68, v251, 46
	v_readlane_b32 s69, v251, 47
	v_readlane_b32 s70, v251, 48
	v_readlane_b32 s71, v251, 49
	s_waitcnt vmcnt(4)
	v_lshlrev_b32_e32 v25, 16, v44
	s_waitcnt vmcnt(3)
	v_mov_b32_e32 v78, v33
	v_and_b32_e32 v77, 0xffff0000, v44
	v_mul_f32_e32 v33, 0xbfb8aa3b, v25
	v_exp_f32_e32 v33, v33
	v_mul_f32_e32 v44, 0xbfb8aa3b, v77
	v_exp_f32_e32 v44, v44
	v_lshlrev_b32_e32 v81, 16, v45
	v_add_f32_e32 v33, 1.0, v33
	v_rcp_f32_e32 v33, v33
	v_add_f32_e32 v44, 1.0, v44
	v_mul_f32_e32 v56, 0xbfb8aa3b, v81
	v_rcp_f32_e32 v79, v44
	v_exp_f32_e32 v44, v56
	v_pk_mul_f32 v[24:25], v[32:33], v[24:25]
	v_and_b32_e32 v45, 0xffff0000, v45
	v_mul_f32_e32 v56, v24, v25
	v_pk_mul_f32 v[24:25], v[78:79], v[76:77]
	s_waitcnt vmcnt(2)
	v_and_b32_e32 v77, 0xffff0000, v54
	v_mul_f32_e32 v58, v24, v25
	v_add_f32_e32 v24, 1.0, v44
	v_rcp_f32_e32 v25, v24
	v_mul_f32_e32 v24, 0xbfb8aa3b, v45
	v_exp_f32_e32 v32, v24
	v_mov_b32_e32 v24, v34
	v_pk_mul_f32 v[24:25], v[24:25], v[80:81]
	v_mul_f32_e32 v44, v27, v53
	v_add_f32_e32 v26, 1.0, v32
	v_rcp_f32_e32 v33, v26
	v_mov_b32_e32 v32, v35
	v_mul_f32_e32 v26, v24, v25
	v_mul_f32_e32 v34, v29, v53
	v_pk_mul_f32 v[24:25], v[32:33], v[44:45]
	v_lshlrev_b32_e32 v45, 16, v54
	v_mul_f32_e32 v25, v24, v25
	v_cvt_pk_bf16_f32 v25, v26, v25
	v_add_co_u32_e32 v26, vcc, s30, v42
	v_cvt_pk_bf16_f32 v24, v56, v58
	v_lshl_add_u64 v[32:33], v[42:43], 0, s[8:9]
	s_nop 0
	v_addc_co_u32_e32 v27, vcc, 0, v43, vcc
	global_store_dwordx2 v[26:27], v[24:25], off
	s_nop 1
	v_mov_b32_e32 v24, v204
	v_mov_b32_e32 v25, v205
	v_mov_b32_e32 v26, v206
	v_mov_b32_e32 v27, v207
	v_mul_f32_e32 v42, v31, v53
	v_lshlrev_b32_e32 v79, 16, v55
	v_and_b32_e32 v55, 0xffff0000, v55
	v_mul_f32_e32 v29, 0xbfb8aa3b, v45
	v_mul_f32_e32 v31, 0xbfb8aa3b, v77
	v_mul_f32_e32 v35, 0xbfb8aa3b, v79
	v_mul_f32_e32 v43, 0xbfb8aa3b, v55
	v_exp_f32_e32 v29, v29
	v_exp_f32_e32 v31, v31
	v_exp_f32_e32 v35, v35
	v_exp_f32_e32 v43, v43
	v_add_f32_e32 v29, 1.0, v29
	v_add_f32_e32 v31, 1.0, v31
	v_add_f32_e32 v44, 1.0, v35
	v_add_f32_e32 v43, 1.0, v43
	v_rcp_f32_e32 v29, v29
	v_rcp_f32_e32 v35, v31
	v_rcp_f32_e32 v31, v44
	v_rcp_f32_e32 v43, v43
	s_waitcnt vmcnt(1)
; __device__ __forceinline__ unsigned cvt_pk(float lo, float hi) { unsigned r; asm("v_cvt_pk_bf16_f32 %0, %1, %2" : "=v"(r) : "v"(lo), "v"(hi)); return r; }
; __device__ __forceinline__ float bflo(unsigned w) { return __uint_as_float(w << 16); }
; __device__ __forceinline__ float bfhi(unsigned w) { return __uint_as_float(w & 0xffff0000u); }
; __device__ __forceinline__ void gla_c_item(unsigned char* lds, const Params& p, int item, bool dry) {
;     ...
;     for (int tb = 0; tb < 4; ++tb) { const int t = 16 * tb + li; float tot = 0.f;
; #pragma unroll
;         for (int w8 = 0; w8 < 8; ++w8) tot += red[w8 * 64 + t];
;         const float rinv = 1.0f / sqrtf(tot * (1.f / 256.f) + LN_EPS);
;         if (t < nvalid && !dry) {
; #pragma unroll
;             for (int v = 0; v < 2; ++v) { const int vdim = 16 * (2 * wave + v) + 4 * fq;
;                 const u32x2 ogw = *(const u32x2*)(P + (size_t)(row0 + t) * NPROJ + C_OG + h * 256 + vdim);
;                 const f32x4 g4 = *(const f32x4*)(gn + vdim);
;                 const float og[4] = {bflo(ogw.x), bfhi(ogw.x), bflo(ogw.y), bfhi(ogw.y)}; float r4[4];
; #pragma unroll
;                 for (int r = 0; r < 4; ++r) r4[r] = o[v][tb][r] * rinv * g4[r] * (og[r] * __builtin_amdgcn_rcpf(1.f + __expf(-og[r])));
;                 u32x2 w; w.x = cvt_pk(r4[0], r4[1]); w.y = cvt_pk(r4[2], r4[3]);
;                 *(u32x2*)(P + (size_t)(row0 + t) * NPROJ + C_VA + h * 256 + vdim) = w; }
	v_mov_b32_e32 v44, v24
	v_mov_b32_e32 v76, v25
	v_mov_b32_e32 v78, v26
	v_mov_b32_e32 v54, v27
	v_pk_mul_f32 v[24:25], v[28:29], v[44:45]
	v_pk_mul_f32 v[26:27], v[34:35], v[76:77]
	v_pk_mul_f32 v[28:29], v[30:31], v[78:79]
	v_pk_mul_f32 v[30:31], v[42:43], v[54:55]
	v_mul_f32_e32 v24, v24, v25
	v_mul_f32_e32 v25, v26, v27
	v_mul_f32_e32 v26, v28, v29
	v_mul_f32_e32 v27, v30, v31
	v_cvt_pk_bf16_f32 v24, v24, v25
	v_cvt_pk_bf16_f32 v25, v26, v27
	global_store_dwordx2 v[32:33], v[24:25], off offset:32
	s_nop 1
	v_mov_b32_e32 v24, v200
	v_mov_b32_e32 v25, v201
	v_mov_b32_e32 v26, v202
	v_mov_b32_e32 v27, v203
	v_add_f32_e32 v28, 0, v57
	v_add_f32_e32 v28, v28, v59
	v_add_f32_e32 v28, v28, v61
	v_add_f32_e32 v28, v28, v63
	v_add_f32_e32 v28, v28, v65
	v_add_f32_e32 v28, v28, v67
	v_add_f32_e32 v28, v28, v69
	v_add_f32_e32 v28, v28, v71
	v_fmamk_f32 v28, v28, 0x3b800000, v49
	v_mul_f32_e32 v29, 0x4f800000, v28
	v_cmp_gt_f32_e32 vcc, s74, v28
	s_nop 1
	v_cndmask_b32_e32 v28, v28, v29, vcc
	v_sqrt_f32_e32 v29, v28
	s_nop 0
	v_add_u32_e32 v30, -1, v29
	v_add_u32_e32 v31, 1, v29
	v_fma_f32 v32, -v30, v29, v28
	v_fma_f32 v33, -v31, v29, v28
	v_cmp_ge_f32_e64 s[0:1], 0, v32
	s_nop 1
	v_cndmask_b32_e64 v29, v29, v30, s[0:1]
	v_cmp_lt_f32_e64 s[0:1], 0, v33
	s_nop 1
	v_cndmask_b32_e64 v29, v29, v31, s[0:1]
	v_mul_f32_e32 v30, 0x37800000, v29
	v_cndmask_b32_e32 v29, v29, v30, vcc
	v_cmp_class_f32_e32 vcc, v28, v50
	s_nop 1
	v_cndmask_b32_e32 v30, v29, v28, vcc
	v_div_scale_f32 v31, s[0:1], v30, v30, 1.0
	v_rcp_f32_e32 v32, v31
	v_add_co_u32_e32 v28, vcc, s30, v46
	v_fma_f32 v34, -v31, v32, 1.0
	s_nop 0
	v_addc_co_u32_e32 v29, vcc, 0, v47, vcc
	v_div_scale_f32 v33, vcc, 1.0, v30, 1.0
	v_fmac_f32_e32 v32, v34, v32
	v_mul_f32_e32 v34, v33, v32
	v_fma_f32 v35, -v31, v34, v33
	v_fmac_f32_e32 v34, v35, v32
	v_fma_f32 v31, -v31, v34, v33
	v_div_fmas_f32 v31, v31, v32, v34
	v_div_fixup_f32 v53, v31, v30, 1.0
	v_mul_f32_e32 v30, v21, v53
	v_lshlrev_b32_e32 v21, 16, v72
	v_and_b32_e32 v31, 0xffff0000, v72
	v_mul_f32_e32 v32, v23, v53
	v_lshlrev_b32_e32 v23, 16, v73
	v_and_b32_e32 v33, 0xffff0000, v73
	v_mul_f32_e32 v34, 0xbfb8aa3b, v21
	v_mul_f32_e32 v35, 0xbfb8aa3b, v31
	v_mul_f32_e32 v42, 0xbfb8aa3b, v23
	v_mul_f32_e32 v43, 0xbfb8aa3b, v33
	v_exp_f32_e32 v34, v34
	v_exp_f32_e32 v35, v35
	v_exp_f32_e32 v42, v42
	v_exp_f32_e32 v43, v43
	v_add_f32_e32 v34, 1.0, v34
	v_add_f32_e32 v44, 1.0, v35
	v_add_f32_e32 v42, 1.0, v42
	v_add_f32_e32 v54, 1.0, v43
	v_rcp_f32_e32 v35, v34
	v_rcp_f32_e32 v43, v44
	v_rcp_f32_e32 v45, v42
	v_rcp_f32_e32 v55, v54
	v_mul_f32_e32 v20, v20, v53
	v_mul_f32_e32 v22, v22, v53
	v_mul_f32_e32 v16, v16, v53
	v_mov_b32_e32 v34, v24
	v_mov_b32_e32 v42, v25
	v_mov_b32_e32 v44, v26
	v_mov_b32_e32 v54, v27
	v_pk_mul_f32 v[20:21], v[34:35], v[20:21]
	v_pk_mul_f32 v[24:25], v[42:43], v[30:31]
	v_pk_mul_f32 v[22:23], v[44:45], v[22:23]
	v_pk_mul_f32 v[26:27], v[54:55], v[32:33]
	v_mul_f32_e32 v20, v20, v21
	v_mul_f32_e32 v21, v24, v25
	v_mul_f32_e32 v22, v22, v23
	v_mul_f32_e32 v23, v26, v27
	v_cvt_pk_bf16_f32 v20, v20, v21
	v_cvt_pk_bf16_f32 v21, v22, v23
	global_store_dwordx2 v[28:29], v[20:21], off
	s_nop 1
	v_mov_b32_e32 v22, v204
	v_mov_b32_e32 v23, v205
	v_mov_b32_e32 v24, v206
	v_mov_b32_e32 v25, v207
	v_lshlrev_b32_e32 v33, 16, v74
	v_and_b32_e32 v35, 0xffff0000, v74
	v_mul_f32_e32 v28, v17, v53
	v_mul_f32_e32 v30, v19, v53
	v_lshlrev_b32_e32 v43, 16, v75
	v_and_b32_e32 v45, 0xffff0000, v75
	v_mul_f32_e32 v17, 0xbfb8aa3b, v33
	v_mul_f32_e32 v19, 0xbfb8aa3b, v35
	v_mul_f32_e32 v21, 0xbfb8aa3b, v43
	v_mul_f32_e32 v29, 0xbfb8aa3b, v45
	v_exp_f32_e32 v17, v17
	v_exp_f32_e32 v19, v19
	v_exp_f32_e32 v21, v21
	v_exp_f32_e32 v29, v29
	v_add_f32_e32 v17, 1.0, v17
	v_add_f32_e32 v19, 1.0, v19
	v_add_f32_e32 v21, 1.0, v21
	v_add_f32_e32 v31, 1.0, v29
	v_rcp_f32_e32 v17, v17
	v_rcp_f32_e32 v29, v19
	v_rcp_f32_e32 v19, v21
	v_rcp_f32_e32 v31, v31
	v_or_b32_e32 v20, 32, v52
	v_mul_f32_e32 v18, v18, v53
	v_lshl_add_u64 v[26:27], v[46:47], 0, s[8:9]
	v_cmp_gt_u32_e32 vcc, s84, v20
	v_mov_b32_e32 v32, v22
	v_mov_b32_e32 v34, v23
	v_mov_b32_e32 v42, v24
	v_mov_b32_e32 v44, v25
	v_pk_mul_f32 v[16:17], v[16:17], v[32:33]
	v_pk_mul_f32 v[22:23], v[28:29], v[34:35]
	v_pk_mul_f32 v[18:19], v[18:19], v[42:43]
	v_pk_mul_f32 v[24:25], v[30:31], v[44:45]
	v_mul_f32_e32 v16, v16, v17
	v_mul_f32_e32 v17, v22, v23
	v_mul_f32_e32 v18, v18, v19
	v_mul_f32_e32 v19, v24, v25
	v_cvt_pk_bf16_f32 v16, v16, v17
	v_cvt_pk_bf16_f32 v17, v18, v19
	global_store_dwordx2 v[26:27], v[16:17], off offset:32
	s_and_saveexec_b64 s[10:11], vcc
	s_cbranch_execz .LBB0_1033
; __device__ __forceinline__ unsigned cvt_pk(float lo, float hi) { unsigned r; asm("v_cvt_pk_bf16_f32 %0, %1, %2" : "=v"(r) : "v"(lo), "v"(hi)); return r; }
; __device__ __forceinline__ float bflo(unsigned w) { return __uint_as_float(w << 16); }
; __device__ __forceinline__ float bfhi(unsigned w) { return __uint_as_float(w & 0xffff0000u); }
; __device__ __forceinline__ void gla_c_item(unsigned char* lds, const Params& p, int item, bool dry) {
;     ...
;     for (int tb = 0; tb < 4; ++tb) { const int t = 16 * tb + li; float tot = 0.f;
; #pragma unroll
;         for (int w8 = 0; w8 < 8; ++w8) tot += red[w8 * 64 + t];
;         const float rinv = 1.0f / sqrtf(tot * (1.f / 256.f) + LN_EPS);
;         if (t < nvalid && !dry) {
; #pragma unroll
;             for (int v = 0; v < 2; ++v) { const int vdim = 16 * (2 * wave + v) + 4 * fq;
;                 const u32x2 ogw = *(const u32x2*)(P + (size_t)(row0 + t) * NPROJ + C_OG + h * 256 + vdim);
;                 const f32x4 g4 = *(const f32x4*)(gn + vdim);
;                 const float og[4] = {bflo(ogw.x), bfhi(ogw.x), bflo(ogw.y), bfhi(ogw.y)}; float r4[4];
; #pragma unroll
;                 for (int r = 0; r < 4; ++r) r4[r] = o[v][tb][r] * rinv * g4[r] * (og[r] * __builtin_amdgcn_rcpf(1.f + __expf(-og[r])));
;                 u32x2 w; w.x = cvt_pk(r4[0], r4[1]); w.y = cvt_pk(r4[2], r4[3]);
;                 *(u32x2*)(P + (size_t)(row0 + t) * NPROJ + C_VA + h * 256 + vdim) = w; }
	v_readlane_b32 s0, v251, 50
	v_readlane_b32 s1, v251, 51
	v_add_u32_e32 v22, s75, v20
	s_nop 1
	v_mov_b32_e32 v16, v200
	v_mov_b32_e32 v17, v201
	v_mov_b32_e32 v18, v202
	v_mov_b32_e32 v19, v203
	v_mov_b64_e32 v[20:21], s[0:1]
	v_mad_i64_i32 v[20:21], s[0:1], v22, s23, v[20:21]
	v_lshl_add_u64 v[20:21], v[20:21], 0, s[6:7]
	v_lshl_add_u64 v[20:21], v[40:41], 1, v[20:21]
	global_load_dwordx2 v[22:23], v[20:21], off offset:2048
	v_add_u32_e32 v30, 0x80, v36
	ds_read2st64_b32 v[24:25], v30 offset0:26 offset1:27
	ds_read2st64_b32 v[26:27], v30 offset0:28 offset1:29
	ds_read2st64_b32 v[28:29], v30 offset0:30 offset1:31
	ds_read2st64_b32 v[30:31], v30 offset0:32 offset1:33
	s_waitcnt lgkmcnt(3)
	v_add_f32_e32 v24, 0, v24
	v_add_f32_e32 v24, v24, v25
	s_waitcnt lgkmcnt(2)
	v_add_f32_e32 v24, v24, v26
	v_add_f32_e32 v24, v24, v27
	s_waitcnt lgkmcnt(1)
	v_add_f32_e32 v24, v24, v28
	v_add_f32_e32 v24, v24, v29
	s_waitcnt lgkmcnt(0)
	v_add_f32_e32 v24, v24, v30
	v_add_f32_e32 v24, v24, v31
	v_fmamk_f32 v24, v24, 0x3b800000, v49
	v_mul_f32_e32 v25, 0x4f800000, v24
	v_cmp_gt_f32_e32 vcc, s74, v24
	v_mov_b32_e32 v34, v19
	v_cndmask_b32_e32 v26, v24, v25, vcc
	v_sqrt_f32_e32 v27, v26
	v_add_co_u32_e64 v24, s[0:1], s30, v20
	v_add_u32_e32 v28, -1, v27
	s_nop 0
	v_addc_co_u32_e64 v25, s[0:1], 0, v21, s[0:1]
	v_add_u32_e32 v29, 1, v27
	v_fma_f32 v30, -v28, v27, v26
	v_fma_f32 v31, -v29, v27, v26
	v_cmp_ge_f32_e64 s[0:1], 0, v30
	s_nop 1
	v_cndmask_b32_e64 v27, v27, v28, s[0:1]
	v_cmp_lt_f32_e64 s[0:1], 0, v31
	s_nop 1
	v_cndmask_b32_e64 v27, v27, v29, s[0:1]
	v_mul_f32_e32 v28, 0x37800000, v27
	v_cndmask_b32_e32 v27, v27, v28, vcc
	v_cmp_class_f32_e32 vcc, v26, v50
	s_nop 1
	v_cndmask_b32_e32 v28, v27, v26, vcc
	v_div_scale_f32 v29, s[0:1], v28, v28, 1.0
	v_rcp_f32_e32 v30, v29
	v_div_scale_f32 v31, vcc, 1.0, v28, 1.0
	global_load_dwordx2 v[26:27], v[20:21], off offset:2080
	v_fma_f32 v32, -v29, v30, 1.0
	v_fmac_f32_e32 v30, v32, v30
	v_mul_f32_e32 v32, v31, v30
	v_fma_f32 v33, -v29, v32, v31
	v_fmac_f32_e32 v32, v33, v30
	v_fma_f32 v29, -v29, v32, v31
	v_div_fmas_f32 v29, v29, v30, v32
	v_div_fixup_f32 v42, v29, v28, 1.0
	v_mul_f32_e32 v28, v13, v42
	s_waitcnt vmcnt(1)
	v_lshlrev_b32_e32 v13, 16, v22
	v_and_b32_e32 v29, 0xffff0000, v22
	v_mul_f32_e32 v30, v15, v42
	v_mov_b32_e32 v32, v17
	v_lshlrev_b32_e32 v15, 16, v23
	v_and_b32_e32 v31, 0xffff0000, v23
	v_mul_f32_e32 v17, 0xbfb8aa3b, v13
	v_mul_f32_e32 v19, 0xbfb8aa3b, v29
	v_mul_f32_e32 v22, 0xbfb8aa3b, v15
	v_mul_f32_e32 v23, 0xbfb8aa3b, v31
	v_exp_f32_e32 v17, v17
	v_exp_f32_e32 v19, v19
	v_exp_f32_e32 v22, v22
	v_exp_f32_e32 v23, v23
	v_add_f32_e32 v17, 1.0, v17
	v_add_f32_e32 v19, 1.0, v19
	v_add_f32_e32 v22, 1.0, v22
	v_add_f32_e32 v23, 1.0, v23
	v_rcp_f32_e32 v17, v17
	v_rcp_f32_e32 v33, v19
	v_rcp_f32_e32 v19, v22
	v_rcp_f32_e32 v35, v23
	v_mul_f32_e32 v12, v12, v42
	v_mul_f32_e32 v14, v14, v42
	v_pk_mul_f32 v[12:13], v[16:17], v[12:13]
	v_pk_mul_f32 v[16:17], v[32:33], v[28:29]
	v_pk_mul_f32 v[14:15], v[18:19], v[14:15]
	v_pk_mul_f32 v[18:19], v[34:35], v[30:31]
	v_mul_f32_e32 v12, v12, v13
	v_mul_f32_e32 v13, v16, v17
	v_mul_f32_e32 v14, v14, v15
	v_mul_f32_e32 v15, v18, v19
	v_cvt_pk_bf16_f32 v12, v12, v13
	v_cvt_pk_bf16_f32 v13, v14, v15
	global_store_dwordx2 v[24:25], v[12:13], off
	s_nop 1
	v_mov_b32_e32 v12, v204
	v_mov_b32_e32 v13, v205
	v_mov_b32_e32 v14, v206
	v_mov_b32_e32 v15, v207
	v_lshl_add_u64 v[16:17], v[20:21], 0, s[8:9]
	v_mul_f32_e32 v18, v9, v42
	v_mul_f32_e32 v20, v11, v42
	v_mul_f32_e32 v8, v8, v42
	v_mul_f32_e32 v10, v10, v42
	s_waitcnt vmcnt(1)
	v_lshlrev_b32_e32 v23, 16, v26
	v_and_b32_e32 v25, 0xffff0000, v26
	v_lshlrev_b32_e32 v29, 16, v27
	v_and_b32_e32 v27, 0xffff0000, v27
	v_mul_f32_e32 v9, 0xbfb8aa3b, v23
	v_mul_f32_e32 v11, 0xbfb8aa3b, v25
	v_mul_f32_e32 v19, 0xbfb8aa3b, v29
	v_mul_f32_e32 v21, 0xbfb8aa3b, v27
	v_exp_f32_e32 v9, v9
	v_exp_f32_e32 v11, v11
	v_exp_f32_e32 v19, v19
	v_exp_f32_e32 v21, v21
	v_add_f32_e32 v9, 1.0, v9
	v_add_f32_e32 v11, 1.0, v11
	v_add_f32_e32 v22, 1.0, v19
	v_add_f32_e32 v21, 1.0, v21
	v_rcp_f32_e32 v9, v9
	v_rcp_f32_e32 v19, v11
	v_rcp_f32_e32 v11, v22
	v_rcp_f32_e32 v21, v21
	v_mov_b32_e32 v22, v12
	v_mov_b32_e32 v24, v13
	v_mov_b32_e32 v28, v14
	v_mov_b32_e32 v26, v15
	v_pk_mul_f32 v[8:9], v[8:9], v[22:23]
	v_pk_mul_f32 v[12:13], v[18:19], v[24:25]
	v_pk_mul_f32 v[10:11], v[10:11], v[28:29]
	v_pk_mul_f32 v[14:15], v[20:21], v[26:27]
	v_mul_f32_e32 v8, v8, v9
	v_mul_f32_e32 v9, v12, v13
	v_mul_f32_e32 v10, v10, v11
	v_mul_f32_e32 v11, v14, v15
	v_cvt_pk_bf16_f32 v8, v8, v9
	v_cvt_pk_bf16_f32 v9, v10, v11
	global_store_dwordx2 v[16:17], v[8:9], off offset:32
; __device__ __forceinline__ unsigned cvt_pk(float lo, float hi) { unsigned r; asm("v_cvt_pk_bf16_f32 %0, %1, %2" : "=v"(r) : "v"(lo), "v"(hi)); return r; }
; __device__ __forceinline__ float bflo(unsigned w) { return __uint_as_float(w << 16); }
; __device__ __forceinline__ float bfhi(unsigned w) { return __uint_as_float(w & 0xffff0000u); }
; __device__ __forceinline__ void gla_c_item(unsigned char* lds, const Params& p, int item, bool dry) {
;     ...
;     for (int tb = 0; tb < 4; ++tb) { const int t = 16 * tb + li; float tot = 0.f;
; #pragma unroll
;         for (int w8 = 0; w8 < 8; ++w8) tot += red[w8 * 64 + t];
;         const float rinv = 1.0f / sqrtf(tot * (1.f / 256.f) + LN_EPS);
;         if (t < nvalid && !dry) {
; #pragma unroll
;             for (int v = 0; v < 2; ++v) { const int vdim = 16 * (2 * wave + v) + 4 * fq;
;                 const u32x2 ogw = *(const u32x2*)(P + (size_t)(row0 + t) * NPROJ + C_OG + h * 256 + vdim);
;                 const f32x4 g4 = *(const f32x4*)(gn + vdim);
;                 const float og[4] = {bflo(ogw.x), bfhi(ogw.x), bflo(ogw.y), bfhi(ogw.y)}; float r4[4];
; #pragma unroll
;                 for (int r = 0; r < 4; ++r) r4[r] = o[v][tb][r] * rinv * g4[r] * (og[r] * __builtin_amdgcn_rcpf(1.f + __expf(-og[r])));
;                 u32x2 w; w.x = cvt_pk(r4[0], r4[1]); w.y = cvt_pk(r4[2], r4[3]);
;                 *(u32x2*)(P + (size_t)(row0 + t) * NPROJ + C_VA + h * 256 + vdim) = w; }
.LBB0_1033:
	s_or_b64 exec, exec, s[10:11]
	v_or_b32_e32 v8, 48, v52
	v_cmp_gt_u32_e32 vcc, s84, v8
	s_and_saveexec_b64 s[10:11], vcc
	s_cbranch_execz .LBB0_959
	v_readlane_b32 s0, v251, 50
	v_readlane_b32 s1, v251, 51
	v_add_u32_e32 v14, s75, v8
	s_nop 1
	v_mov_b32_e32 v8, v200
	v_mov_b32_e32 v9, v201
	v_mov_b32_e32 v10, v202
	v_mov_b32_e32 v11, v203
	v_mov_b64_e32 v[12:13], s[0:1]
	v_mad_i64_i32 v[12:13], s[0:1], v14, s23, v[12:13]
	v_lshl_add_u64 v[12:13], v[12:13], 0, s[6:7]
	v_lshl_add_u64 v[12:13], v[40:41], 1, v[12:13]
	global_load_dwordx2 v[14:15], v[12:13], off offset:2048
	v_add_u32_e32 v22, 0xc0, v36
	ds_read2st64_b32 v[16:17], v22 offset0:26 offset1:27
	ds_read2st64_b32 v[18:19], v22 offset0:28 offset1:29
	ds_read2st64_b32 v[20:21], v22 offset0:30 offset1:31
	ds_read2st64_b32 v[22:23], v22 offset0:32 offset1:33
	s_waitcnt lgkmcnt(3)
	v_add_f32_e32 v16, 0, v16
	v_add_f32_e32 v16, v16, v17
	s_waitcnt lgkmcnt(2)
	v_add_f32_e32 v16, v16, v18
	v_add_f32_e32 v16, v16, v19
	s_waitcnt lgkmcnt(1)
	v_add_f32_e32 v16, v16, v20
	v_add_f32_e32 v16, v16, v21
	s_waitcnt lgkmcnt(0)
	v_add_f32_e32 v16, v16, v22
	v_add_f32_e32 v16, v16, v23
	v_fmamk_f32 v16, v16, 0x3b800000, v49
	v_mul_f32_e32 v17, 0x4f800000, v16
	v_cmp_gt_f32_e32 vcc, s74, v16
	v_mov_b32_e32 v26, v11
	v_cndmask_b32_e32 v18, v16, v17, vcc
	v_sqrt_f32_e32 v19, v18
	v_add_co_u32_e64 v16, s[0:1], s30, v12
	v_add_u32_e32 v20, -1, v19
	s_nop 0
	v_addc_co_u32_e64 v17, s[0:1], 0, v13, s[0:1]
	v_add_u32_e32 v21, 1, v19
	v_fma_f32 v22, -v20, v19, v18
	v_fma_f32 v23, -v21, v19, v18
	v_cmp_ge_f32_e64 s[0:1], 0, v22
	s_nop 1
	v_cndmask_b32_e64 v19, v19, v20, s[0:1]
	v_cmp_lt_f32_e64 s[0:1], 0, v23
	s_nop 1
	v_cndmask_b32_e64 v19, v19, v21, s[0:1]
	v_mul_f32_e32 v20, 0x37800000, v19
	v_cndmask_b32_e32 v19, v19, v20, vcc
	v_cmp_class_f32_e32 vcc, v18, v50
	s_nop 1
	v_cndmask_b32_e32 v20, v19, v18, vcc
	v_div_scale_f32 v21, s[0:1], v20, v20, 1.0
	v_rcp_f32_e32 v22, v21
	v_div_scale_f32 v23, vcc, 1.0, v20, 1.0
	global_load_dwordx2 v[18:19], v[12:13], off offset:2080
	v_fma_f32 v24, -v21, v22, 1.0
	v_fmac_f32_e32 v22, v24, v22
	v_mul_f32_e32 v24, v23, v22
	v_fma_f32 v25, -v21, v24, v23
	v_fmac_f32_e32 v24, v25, v22
	v_fma_f32 v21, -v21, v24, v23
	v_div_fmas_f32 v21, v21, v22, v24
	v_div_fixup_f32 v28, v21, v20, 1.0
	v_mul_f32_e32 v20, v5, v28
	s_waitcnt vmcnt(1)
	v_lshlrev_b32_e32 v5, 16, v14
	v_and_b32_e32 v21, 0xffff0000, v14
	v_mul_f32_e32 v22, v7, v28
	v_mov_b32_e32 v24, v9
	v_lshlrev_b32_e32 v7, 16, v15
	v_and_b32_e32 v23, 0xffff0000, v15
	v_mul_f32_e32 v9, 0xbfb8aa3b, v5
	v_mul_f32_e32 v11, 0xbfb8aa3b, v21
	v_mul_f32_e32 v14, 0xbfb8aa3b, v7
	v_mul_f32_e32 v15, 0xbfb8aa3b, v23
	v_exp_f32_e32 v9, v9
	v_exp_f32_e32 v11, v11
	v_exp_f32_e32 v14, v14
	v_exp_f32_e32 v15, v15
	v_add_f32_e32 v9, 1.0, v9
	v_add_f32_e32 v11, 1.0, v11
	v_add_f32_e32 v14, 1.0, v14
	v_add_f32_e32 v15, 1.0, v15
	v_rcp_f32_e32 v9, v9
	v_rcp_f32_e32 v25, v11
	v_rcp_f32_e32 v11, v14
	v_rcp_f32_e32 v27, v15
	v_mul_f32_e32 v4, v4, v28
	v_mul_f32_e32 v6, v6, v28
	v_pk_mul_f32 v[4:5], v[8:9], v[4:5]
	v_pk_mul_f32 v[8:9], v[24:25], v[20:21]
	v_pk_mul_f32 v[6:7], v[10:11], v[6:7]
	v_pk_mul_f32 v[10:11], v[26:27], v[22:23]
	v_mul_f32_e32 v4, v4, v5
	v_mul_f32_e32 v5, v8, v9
	v_mul_f32_e32 v6, v6, v7
	v_mul_f32_e32 v7, v10, v11
	v_cvt_pk_bf16_f32 v4, v4, v5
	v_cvt_pk_bf16_f32 v5, v6, v7
	global_store_dwordx2 v[16:17], v[4:5], off
	s_nop 1
	v_mov_b32_e32 v4, v204
	v_mov_b32_e32 v5, v205
	v_mov_b32_e32 v6, v206
	v_mov_b32_e32 v7, v207
	v_lshl_add_u64 v[8:9], v[12:13], 0, s[8:9]
	v_mul_f32_e32 v10, v1, v28
	v_mul_f32_e32 v12, v3, v28
	v_mul_f32_e32 v0, v0, v28
	v_mul_f32_e32 v2, v2, v28
	s_waitcnt vmcnt(1)
	v_lshlrev_b32_e32 v15, 16, v18
	v_and_b32_e32 v17, 0xffff0000, v18
	v_lshlrev_b32_e32 v21, 16, v19
	v_and_b32_e32 v19, 0xffff0000, v19
	v_mul_f32_e32 v1, 0xbfb8aa3b, v15
	v_mul_f32_e32 v3, 0xbfb8aa3b, v17
	v_mul_f32_e32 v11, 0xbfb8aa3b, v21
	v_mul_f32_e32 v13, 0xbfb8aa3b, v19
	v_exp_f32_e32 v1, v1
	v_exp_f32_e32 v3, v3
	v_exp_f32_e32 v11, v11
	v_exp_f32_e32 v13, v13
	v_add_f32_e32 v1, 1.0, v1
	v_add_f32_e32 v3, 1.0, v3
	v_add_f32_e32 v14, 1.0, v11
	v_add_f32_e32 v13, 1.0, v13
	v_rcp_f32_e32 v1, v1
	v_rcp_f32_e32 v11, v3
	v_rcp_f32_e32 v3, v14
	v_rcp_f32_e32 v13, v13
	v_mov_b32_e32 v14, v4
	v_mov_b32_e32 v16, v5
	v_mov_b32_e32 v20, v6
	v_mov_b32_e32 v18, v7
	v_pk_mul_f32 v[0:1], v[0:1], v[14:15]
	v_pk_mul_f32 v[4:5], v[10:11], v[16:17]
	v_pk_mul_f32 v[2:3], v[2:3], v[20:21]
	v_pk_mul_f32 v[6:7], v[12:13], v[18:19]
	v_mul_f32_e32 v0, v0, v1
	v_mul_f32_e32 v1, v4, v5
	v_mul_f32_e32 v2, v2, v3
	v_mul_f32_e32 v3, v6, v7
	v_cvt_pk_bf16_f32 v0, v0, v1
	v_cvt_pk_bf16_f32 v1, v2, v3
	global_store_dwordx2 v[8:9], v[0:1], off offset:32
	s_branch .LBB0_959
